# final normalise+store section rewritten: adjacent lane pairs exchange halves (DPP) so each output store covers 32 contiguous bytes per lane pair
# speedup vs baseline: 1.0161x; 1.0064x over previous
.LBB0_663:
	s_or_b64 exec, exec, s[4:5]
	v_lshl_add_u64 v[0:1], s[24:25], 0, v[194:195]
	s_mov_b64 s[0:1], 0x2b04600
	s_waitcnt lgkmcnt(0)
	v_lshl_add_u64 v[2:3], v[0:1], 0, s[0:1]
	v_add_co_u32_e32 v0, vcc, 0x2b04000, v0
	s_waitcnt lgkmcnt(0)
	s_barrier
	s_nop 0
	v_addc_co_u32_e32 v1, vcc, 0, v1, vcc
	flat_load_dwordx4 v[8:11], v[2:3] offset:16
	flat_load_dwordx4 v[4:7], v[2:3] offset:512
	flat_load_dwordx4 v[12:15], v[0:1] offset:1536
	flat_load_dwordx4 v[84:87], v[2:3] offset:528
	v_lshl_add_u32 v233, v204, 2, 0
	v_add_u32_e32 v233, 0x1000, v233
	ds_read2_b32 v[88:89], v233 offset1:16
	ds_read2_b32 v[92:93], v233 offset0:32 offset1:48
	ds_read2_b32 v[96:97], v233 offset0:128 offset1:144
	ds_read2_b32 v[100:101], v233 offset0:160 offset1:176
	v_mbcnt_lo_u32_b32 v232, -1, 0
	v_mbcnt_hi_u32_b32 v232, -1, v232
	v_and_b32_e32 v232, 1, v232
	v_cmp_eq_u32_e64 s[8:9], 0, v232
	s_nop 3
	v_mov_b32_e32 v228, 0xffffe010
	v_mov_b32_e32 v229, -1
	v_mov_b32_e32 v233, 0x2010
	v_cndmask_b32_e64 v228, v228, 0, s[8:9]
	v_cndmask_b32_e64 v229, v229, 0, s[8:9]
	v_cndmask_b32_e64 v230, 0, v233, s[8:9]
	v_mov_b32_e32 v231, 0
	s_waitcnt lgkmcnt(0)
	v_mov_b32_e32 v90, v89
	v_mov_b32_e32 v94, v93
	v_mov_b32_e32 v98, v97
	v_mov_b32_e32 v102, v101
	s_waitcnt vmcnt(0)
	v_lshl_add_u64 v[222:223], s[6:7], 0, v[198:199]
	v_lshl_add_u64 v[222:223], v[222:223], 0, v[194:195]
	v_lshl_add_u64 v[224:225], v[222:223], 0, v[228:229]
	v_lshl_add_u64 v[226:227], v[222:223], 0, v[230:231]
	v_pk_mul_f32 v[108:109], v[122:123], v[88:89] op_sel_hi:[1,0]
	v_pk_mul_f32 v[110:111], v[124:125], v[88:89] op_sel_hi:[1,0]
	v_pk_mul_f32 v[104:105], v[126:127], v[88:89] op_sel_hi:[1,0]
	v_pk_mul_f32 v[106:107], v[128:129], v[88:89] op_sel_hi:[1,0]
	v_pk_mul_f32 v[108:109], v[8:9], v[108:109]
	v_pk_mul_f32 v[110:111], v[10:11], v[110:111]
	v_pk_mul_f32 v[104:105], v[12:13], v[104:105]
	v_pk_mul_f32 v[106:107], v[14:15], v[106:107]
	s_nop 1
	v_mov_b32_dpp v130, v108 quad_perm:[1,0,3,2] row_mask:0xf bank_mask:0xf
	v_mov_b32_dpp v131, v109 quad_perm:[1,0,3,2] row_mask:0xf bank_mask:0xf
	v_mov_b32_dpp v132, v110 quad_perm:[1,0,3,2] row_mask:0xf bank_mask:0xf
	v_mov_b32_dpp v133, v111 quad_perm:[1,0,3,2] row_mask:0xf bank_mask:0xf
	s_nop 0
	v_cndmask_b32_e64 v134, v130, v104, s[8:9]
	v_cndmask_b32_e64 v138, v104, v130, s[8:9]
	v_cndmask_b32_e64 v135, v131, v105, s[8:9]
	v_cndmask_b32_e64 v139, v105, v131, s[8:9]
	v_cndmask_b32_e64 v136, v132, v106, s[8:9]
	v_cndmask_b32_e64 v140, v106, v132, s[8:9]
	v_cndmask_b32_e64 v137, v133, v107, s[8:9]
	v_cndmask_b32_e64 v141, v107, v133, s[8:9]
	global_store_dwordx4 v[224:225], v[134:137], off
	global_store_dwordx4 v[226:227], v[138:141], off
	v_pk_mul_f32 v[206:207], v[114:115], v[88:89] op_sel_hi:[1,0]
	v_pk_mul_f32 v[208:209], v[116:117], v[88:89] op_sel_hi:[1,0]
	v_pk_mul_f32 v[142:143], v[118:119], v[88:89] op_sel_hi:[1,0]
	v_pk_mul_f32 v[144:145], v[120:121], v[88:89] op_sel_hi:[1,0]
	v_pk_mul_f32 v[206:207], v[84:85], v[206:207]
	v_pk_mul_f32 v[208:209], v[86:87], v[208:209]
	v_pk_mul_f32 v[142:143], v[4:5], v[142:143]
	v_pk_mul_f32 v[144:145], v[6:7], v[144:145]
	s_nop 1
	v_mov_b32_dpp v210, v206 quad_perm:[1,0,3,2] row_mask:0xf bank_mask:0xf
	v_mov_b32_dpp v211, v207 quad_perm:[1,0,3,2] row_mask:0xf bank_mask:0xf
	v_mov_b32_dpp v212, v208 quad_perm:[1,0,3,2] row_mask:0xf bank_mask:0xf
	v_mov_b32_dpp v213, v209 quad_perm:[1,0,3,2] row_mask:0xf bank_mask:0xf
	s_nop 0
	v_cndmask_b32_e64 v214, v210, v142, s[8:9]
	v_cndmask_b32_e64 v218, v142, v210, s[8:9]
	v_cndmask_b32_e64 v215, v211, v143, s[8:9]
	v_cndmask_b32_e64 v219, v143, v211, s[8:9]
	v_cndmask_b32_e64 v216, v212, v144, s[8:9]
	v_cndmask_b32_e64 v220, v144, v212, s[8:9]
	v_cndmask_b32_e64 v217, v213, v145, s[8:9]
	v_cndmask_b32_e64 v221, v145, v213, s[8:9]
	global_store_dwordx4 v[224:225], v[214:217], off offset:512
	global_store_dwordx4 v[226:227], v[218:221], off offset:512
	v_add_u32_e32 v222, 0x10, v196
	v_ashrrev_i32_e32 v223, 31, v222
	v_lshlrev_b64 v[222:223], 13, v[222:223]
	v_lshl_add_u64 v[222:223], s[6:7], 0, v[222:223]
	v_lshl_add_u64 v[222:223], v[222:223], 0, v[194:195]
	v_lshl_add_u64 v[224:225], v[222:223], 0, v[228:229]
	v_lshl_add_u64 v[226:227], v[222:223], 0, v[230:231]
	v_pk_mul_f32 v[108:109], v[186:187], v[90:91] op_sel_hi:[1,0]
	v_pk_mul_f32 v[110:111], v[188:189], v[90:91] op_sel_hi:[1,0]
	v_pk_mul_f32 v[104:105], v[190:191], v[90:91] op_sel_hi:[1,0]
	v_pk_mul_f32 v[106:107], v[192:193], v[90:91] op_sel_hi:[1,0]
	v_pk_mul_f32 v[108:109], v[8:9], v[108:109]
	v_pk_mul_f32 v[110:111], v[10:11], v[110:111]
	v_pk_mul_f32 v[104:105], v[12:13], v[104:105]
	v_pk_mul_f32 v[106:107], v[14:15], v[106:107]
	s_nop 1
	v_mov_b32_dpp v130, v108 quad_perm:[1,0,3,2] row_mask:0xf bank_mask:0xf
	v_mov_b32_dpp v131, v109 quad_perm:[1,0,3,2] row_mask:0xf bank_mask:0xf
	v_mov_b32_dpp v132, v110 quad_perm:[1,0,3,2] row_mask:0xf bank_mask:0xf
	v_mov_b32_dpp v133, v111 quad_perm:[1,0,3,2] row_mask:0xf bank_mask:0xf
	s_nop 0
	v_cndmask_b32_e64 v134, v130, v104, s[8:9]
	v_cndmask_b32_e64 v138, v104, v130, s[8:9]
	v_cndmask_b32_e64 v135, v131, v105, s[8:9]
	v_cndmask_b32_e64 v139, v105, v131, s[8:9]
	v_cndmask_b32_e64 v136, v132, v106, s[8:9]
	v_cndmask_b32_e64 v140, v106, v132, s[8:9]
	v_cndmask_b32_e64 v137, v133, v107, s[8:9]
	v_cndmask_b32_e64 v141, v107, v133, s[8:9]
	global_store_dwordx4 v[224:225], v[134:137], off
	global_store_dwordx4 v[226:227], v[138:141], off
	v_pk_mul_f32 v[206:207], v[178:179], v[90:91] op_sel_hi:[1,0]
	v_pk_mul_f32 v[208:209], v[180:181], v[90:91] op_sel_hi:[1,0]
	v_pk_mul_f32 v[142:143], v[182:183], v[90:91] op_sel_hi:[1,0]
	v_pk_mul_f32 v[144:145], v[184:185], v[90:91] op_sel_hi:[1,0]
	v_pk_mul_f32 v[206:207], v[84:85], v[206:207]
	v_pk_mul_f32 v[208:209], v[86:87], v[208:209]
	v_pk_mul_f32 v[142:143], v[4:5], v[142:143]
	v_pk_mul_f32 v[144:145], v[6:7], v[144:145]
	s_nop 1
	v_mov_b32_dpp v210, v206 quad_perm:[1,0,3,2] row_mask:0xf bank_mask:0xf
	v_mov_b32_dpp v211, v207 quad_perm:[1,0,3,2] row_mask:0xf bank_mask:0xf
	v_mov_b32_dpp v212, v208 quad_perm:[1,0,3,2] row_mask:0xf bank_mask:0xf
	v_mov_b32_dpp v213, v209 quad_perm:[1,0,3,2] row_mask:0xf bank_mask:0xf
	s_nop 0
	v_cndmask_b32_e64 v214, v210, v142, s[8:9]
	v_cndmask_b32_e64 v218, v142, v210, s[8:9]
	v_cndmask_b32_e64 v215, v211, v143, s[8:9]
	v_cndmask_b32_e64 v219, v143, v211, s[8:9]
	v_cndmask_b32_e64 v216, v212, v144, s[8:9]
	v_cndmask_b32_e64 v220, v144, v212, s[8:9]
	v_cndmask_b32_e64 v217, v213, v145, s[8:9]
	v_cndmask_b32_e64 v221, v145, v213, s[8:9]
	global_store_dwordx4 v[224:225], v[214:217], off offset:512
	global_store_dwordx4 v[226:227], v[218:221], off offset:512
	v_add_u32_e32 v222, 0x20, v196
	v_ashrrev_i32_e32 v223, 31, v222
	v_lshlrev_b64 v[222:223], 13, v[222:223]
	v_lshl_add_u64 v[222:223], s[6:7], 0, v[222:223]
	v_lshl_add_u64 v[222:223], v[222:223], 0, v[194:195]
	v_lshl_add_u64 v[224:225], v[222:223], 0, v[228:229]
	v_lshl_add_u64 v[226:227], v[222:223], 0, v[230:231]
	v_pk_mul_f32 v[108:109], v[170:171], v[92:93] op_sel_hi:[1,0]
	v_pk_mul_f32 v[110:111], v[172:173], v[92:93] op_sel_hi:[1,0]
	v_pk_mul_f32 v[104:105], v[174:175], v[92:93] op_sel_hi:[1,0]
	v_pk_mul_f32 v[106:107], v[176:177], v[92:93] op_sel_hi:[1,0]
	v_pk_mul_f32 v[108:109], v[8:9], v[108:109]
	v_pk_mul_f32 v[110:111], v[10:11], v[110:111]
	v_pk_mul_f32 v[104:105], v[12:13], v[104:105]
	v_pk_mul_f32 v[106:107], v[14:15], v[106:107]
	s_nop 1
	v_mov_b32_dpp v130, v108 quad_perm:[1,0,3,2] row_mask:0xf bank_mask:0xf
	v_mov_b32_dpp v131, v109 quad_perm:[1,0,3,2] row_mask:0xf bank_mask:0xf
	v_mov_b32_dpp v132, v110 quad_perm:[1,0,3,2] row_mask:0xf bank_mask:0xf
	v_mov_b32_dpp v133, v111 quad_perm:[1,0,3,2] row_mask:0xf bank_mask:0xf
	s_nop 0
	v_cndmask_b32_e64 v134, v130, v104, s[8:9]
	v_cndmask_b32_e64 v138, v104, v130, s[8:9]
	v_cndmask_b32_e64 v135, v131, v105, s[8:9]
	v_cndmask_b32_e64 v139, v105, v131, s[8:9]
	v_cndmask_b32_e64 v136, v132, v106, s[8:9]
	v_cndmask_b32_e64 v140, v106, v132, s[8:9]
	v_cndmask_b32_e64 v137, v133, v107, s[8:9]
	v_cndmask_b32_e64 v141, v107, v133, s[8:9]
	global_store_dwordx4 v[224:225], v[134:137], off
	global_store_dwordx4 v[226:227], v[138:141], off
	v_pk_mul_f32 v[206:207], v[162:163], v[92:93] op_sel_hi:[1,0]
	v_pk_mul_f32 v[208:209], v[164:165], v[92:93] op_sel_hi:[1,0]
	v_pk_mul_f32 v[142:143], v[200:201], v[92:93] op_sel_hi:[1,0]
	v_pk_mul_f32 v[144:145], v[168:169], v[92:93] op_sel_hi:[1,0]
	v_pk_mul_f32 v[206:207], v[84:85], v[206:207]
	v_pk_mul_f32 v[208:209], v[86:87], v[208:209]
	v_pk_mul_f32 v[142:143], v[4:5], v[142:143]
	v_pk_mul_f32 v[144:145], v[6:7], v[144:145]
	s_nop 1
	v_mov_b32_dpp v210, v206 quad_perm:[1,0,3,2] row_mask:0xf bank_mask:0xf
	v_mov_b32_dpp v211, v207 quad_perm:[1,0,3,2] row_mask:0xf bank_mask:0xf
	v_mov_b32_dpp v212, v208 quad_perm:[1,0,3,2] row_mask:0xf bank_mask:0xf
	v_mov_b32_dpp v213, v209 quad_perm:[1,0,3,2] row_mask:0xf bank_mask:0xf
	s_nop 0
	v_cndmask_b32_e64 v214, v210, v142, s[8:9]
	v_cndmask_b32_e64 v218, v142, v210, s[8:9]
	v_cndmask_b32_e64 v215, v211, v143, s[8:9]
	v_cndmask_b32_e64 v219, v143, v211, s[8:9]
	v_cndmask_b32_e64 v216, v212, v144, s[8:9]
	v_cndmask_b32_e64 v220, v144, v212, s[8:9]
	v_cndmask_b32_e64 v217, v213, v145, s[8:9]
	v_cndmask_b32_e64 v221, v145, v213, s[8:9]
	global_store_dwordx4 v[224:225], v[214:217], off offset:512
	global_store_dwordx4 v[226:227], v[218:221], off offset:512
	v_add_u32_e32 v222, 0x30, v196
	v_ashrrev_i32_e32 v223, 31, v222
	v_lshlrev_b64 v[222:223], 13, v[222:223]
	v_lshl_add_u64 v[222:223], s[6:7], 0, v[222:223]
	v_lshl_add_u64 v[222:223], v[222:223], 0, v[194:195]
	v_lshl_add_u64 v[224:225], v[222:223], 0, v[228:229]
	v_lshl_add_u64 v[226:227], v[222:223], 0, v[230:231]
	v_pk_mul_f32 v[108:109], v[154:155], v[94:95] op_sel_hi:[1,0]
	v_pk_mul_f32 v[110:111], v[156:157], v[94:95] op_sel_hi:[1,0]
	v_pk_mul_f32 v[104:105], v[158:159], v[94:95] op_sel_hi:[1,0]
	v_pk_mul_f32 v[106:107], v[160:161], v[94:95] op_sel_hi:[1,0]
	v_pk_mul_f32 v[108:109], v[8:9], v[108:109]
	v_pk_mul_f32 v[110:111], v[10:11], v[110:111]
	v_pk_mul_f32 v[104:105], v[12:13], v[104:105]
	v_pk_mul_f32 v[106:107], v[14:15], v[106:107]
	s_nop 1
	v_mov_b32_dpp v130, v108 quad_perm:[1,0,3,2] row_mask:0xf bank_mask:0xf
	v_mov_b32_dpp v131, v109 quad_perm:[1,0,3,2] row_mask:0xf bank_mask:0xf
	v_mov_b32_dpp v132, v110 quad_perm:[1,0,3,2] row_mask:0xf bank_mask:0xf
	v_mov_b32_dpp v133, v111 quad_perm:[1,0,3,2] row_mask:0xf bank_mask:0xf
	s_nop 0
	v_cndmask_b32_e64 v134, v130, v104, s[8:9]
	v_cndmask_b32_e64 v138, v104, v130, s[8:9]
	v_cndmask_b32_e64 v135, v131, v105, s[8:9]
	v_cndmask_b32_e64 v139, v105, v131, s[8:9]
	v_cndmask_b32_e64 v136, v132, v106, s[8:9]
	v_cndmask_b32_e64 v140, v106, v132, s[8:9]
	v_cndmask_b32_e64 v137, v133, v107, s[8:9]
	v_cndmask_b32_e64 v141, v107, v133, s[8:9]
	global_store_dwordx4 v[224:225], v[134:137], off
	global_store_dwordx4 v[226:227], v[138:141], off
	v_pk_mul_f32 v[206:207], v[146:147], v[94:95] op_sel_hi:[1,0]
	v_pk_mul_f32 v[208:209], v[148:149], v[94:95] op_sel_hi:[1,0]
	v_pk_mul_f32 v[142:143], v[150:151], v[94:95] op_sel_hi:[1,0]
	v_pk_mul_f32 v[144:145], v[152:153], v[94:95] op_sel_hi:[1,0]
	v_pk_mul_f32 v[206:207], v[84:85], v[206:207]
	v_pk_mul_f32 v[208:209], v[86:87], v[208:209]
	v_pk_mul_f32 v[142:143], v[4:5], v[142:143]
	v_pk_mul_f32 v[144:145], v[6:7], v[144:145]
	s_nop 1
	v_mov_b32_dpp v210, v206 quad_perm:[1,0,3,2] row_mask:0xf bank_mask:0xf
	v_mov_b32_dpp v211, v207 quad_perm:[1,0,3,2] row_mask:0xf bank_mask:0xf
	v_mov_b32_dpp v212, v208 quad_perm:[1,0,3,2] row_mask:0xf bank_mask:0xf
	v_mov_b32_dpp v213, v209 quad_perm:[1,0,3,2] row_mask:0xf bank_mask:0xf
	s_nop 0
	v_cndmask_b32_e64 v214, v210, v142, s[8:9]
	v_cndmask_b32_e64 v218, v142, v210, s[8:9]
	v_cndmask_b32_e64 v215, v211, v143, s[8:9]
	v_cndmask_b32_e64 v219, v143, v211, s[8:9]
	v_cndmask_b32_e64 v216, v212, v144, s[8:9]
	v_cndmask_b32_e64 v220, v144, v212, s[8:9]
	v_cndmask_b32_e64 v217, v213, v145, s[8:9]
	v_cndmask_b32_e64 v221, v145, v213, s[8:9]
	global_store_dwordx4 v[224:225], v[214:217], off offset:512
	global_store_dwordx4 v[226:227], v[218:221], off offset:512
	v_lshl_add_u64 v[222:223], s[6:7], 0, v[166:167]
	v_lshl_add_u64 v[222:223], v[222:223], 0, v[194:195]
	v_lshl_add_u64 v[224:225], v[222:223], 0, v[228:229]
	v_lshl_add_u64 v[226:227], v[222:223], 0, v[230:231]
	v_pk_mul_f32 v[108:109], v[58:59], v[96:97] op_sel_hi:[1,0]
	v_pk_mul_f32 v[110:111], v[60:61], v[96:97] op_sel_hi:[1,0]
	v_pk_mul_f32 v[104:105], v[62:63], v[96:97] op_sel_hi:[1,0]
	v_pk_mul_f32 v[106:107], v[64:65], v[96:97] op_sel_hi:[1,0]
	v_pk_mul_f32 v[108:109], v[8:9], v[108:109]
	v_pk_mul_f32 v[110:111], v[10:11], v[110:111]
	v_pk_mul_f32 v[104:105], v[12:13], v[104:105]
	v_pk_mul_f32 v[106:107], v[14:15], v[106:107]
	s_nop 1
	v_mov_b32_dpp v130, v108 quad_perm:[1,0,3,2] row_mask:0xf bank_mask:0xf
	v_mov_b32_dpp v131, v109 quad_perm:[1,0,3,2] row_mask:0xf bank_mask:0xf
	v_mov_b32_dpp v132, v110 quad_perm:[1,0,3,2] row_mask:0xf bank_mask:0xf
	v_mov_b32_dpp v133, v111 quad_perm:[1,0,3,2] row_mask:0xf bank_mask:0xf
	s_nop 0
	v_cndmask_b32_e64 v134, v130, v104, s[8:9]
	v_cndmask_b32_e64 v138, v104, v130, s[8:9]
	v_cndmask_b32_e64 v135, v131, v105, s[8:9]
	v_cndmask_b32_e64 v139, v105, v131, s[8:9]
	v_cndmask_b32_e64 v136, v132, v106, s[8:9]
	v_cndmask_b32_e64 v140, v106, v132, s[8:9]
	v_cndmask_b32_e64 v137, v133, v107, s[8:9]
	v_cndmask_b32_e64 v141, v107, v133, s[8:9]
	global_store_dwordx4 v[224:225], v[134:137], off
	global_store_dwordx4 v[226:227], v[138:141], off
	v_pk_mul_f32 v[206:207], v[50:51], v[96:97] op_sel_hi:[1,0]
	v_pk_mul_f32 v[208:209], v[52:53], v[96:97] op_sel_hi:[1,0]
	v_pk_mul_f32 v[142:143], v[54:55], v[96:97] op_sel_hi:[1,0]
	v_pk_mul_f32 v[144:145], v[56:57], v[96:97] op_sel_hi:[1,0]
	v_pk_mul_f32 v[206:207], v[84:85], v[206:207]
	v_pk_mul_f32 v[208:209], v[86:87], v[208:209]
	v_pk_mul_f32 v[142:143], v[4:5], v[142:143]
	v_pk_mul_f32 v[144:145], v[6:7], v[144:145]
	s_nop 1
	v_mov_b32_dpp v210, v206 quad_perm:[1,0,3,2] row_mask:0xf bank_mask:0xf
	v_mov_b32_dpp v211, v207 quad_perm:[1,0,3,2] row_mask:0xf bank_mask:0xf
	v_mov_b32_dpp v212, v208 quad_perm:[1,0,3,2] row_mask:0xf bank_mask:0xf
	v_mov_b32_dpp v213, v209 quad_perm:[1,0,3,2] row_mask:0xf bank_mask:0xf
	s_nop 0
	v_cndmask_b32_e64 v214, v210, v142, s[8:9]
	v_cndmask_b32_e64 v218, v142, v210, s[8:9]
	v_cndmask_b32_e64 v215, v211, v143, s[8:9]
	v_cndmask_b32_e64 v219, v143, v211, s[8:9]
	v_cndmask_b32_e64 v216, v212, v144, s[8:9]
	v_cndmask_b32_e64 v220, v144, v212, s[8:9]
	v_cndmask_b32_e64 v217, v213, v145, s[8:9]
	v_cndmask_b32_e64 v221, v145, v213, s[8:9]
	global_store_dwordx4 v[224:225], v[214:217], off offset:512
	global_store_dwordx4 v[226:227], v[218:221], off offset:512
	v_add_u32_e32 v222, 0x90, v196
	v_ashrrev_i32_e32 v223, 31, v222
	v_lshlrev_b64 v[222:223], 13, v[222:223]
	v_lshl_add_u64 v[222:223], s[6:7], 0, v[222:223]
	v_lshl_add_u64 v[222:223], v[222:223], 0, v[194:195]
	v_lshl_add_u64 v[224:225], v[222:223], 0, v[228:229]
	v_lshl_add_u64 v[226:227], v[222:223], 0, v[230:231]
	v_pk_mul_f32 v[108:109], v[42:43], v[98:99] op_sel_hi:[1,0]
	v_pk_mul_f32 v[110:111], v[44:45], v[98:99] op_sel_hi:[1,0]
	v_pk_mul_f32 v[104:105], v[46:47], v[98:99] op_sel_hi:[1,0]
	v_pk_mul_f32 v[106:107], v[48:49], v[98:99] op_sel_hi:[1,0]
	v_pk_mul_f32 v[108:109], v[8:9], v[108:109]
	v_pk_mul_f32 v[110:111], v[10:11], v[110:111]
	v_pk_mul_f32 v[104:105], v[12:13], v[104:105]
	v_pk_mul_f32 v[106:107], v[14:15], v[106:107]
	s_nop 1
	v_mov_b32_dpp v130, v108 quad_perm:[1,0,3,2] row_mask:0xf bank_mask:0xf
	v_mov_b32_dpp v131, v109 quad_perm:[1,0,3,2] row_mask:0xf bank_mask:0xf
	v_mov_b32_dpp v132, v110 quad_perm:[1,0,3,2] row_mask:0xf bank_mask:0xf
	v_mov_b32_dpp v133, v111 quad_perm:[1,0,3,2] row_mask:0xf bank_mask:0xf
	s_nop 0
	v_cndmask_b32_e64 v134, v130, v104, s[8:9]
	v_cndmask_b32_e64 v138, v104, v130, s[8:9]
	v_cndmask_b32_e64 v135, v131, v105, s[8:9]
	v_cndmask_b32_e64 v139, v105, v131, s[8:9]
	v_cndmask_b32_e64 v136, v132, v106, s[8:9]
	v_cndmask_b32_e64 v140, v106, v132, s[8:9]
	v_cndmask_b32_e64 v137, v133, v107, s[8:9]
	v_cndmask_b32_e64 v141, v107, v133, s[8:9]
	global_store_dwordx4 v[224:225], v[134:137], off
	global_store_dwordx4 v[226:227], v[138:141], off
	v_pk_mul_f32 v[206:207], v[34:35], v[98:99] op_sel_hi:[1,0]
	v_pk_mul_f32 v[208:209], v[36:37], v[98:99] op_sel_hi:[1,0]
	v_pk_mul_f32 v[142:143], v[38:39], v[98:99] op_sel_hi:[1,0]
	v_pk_mul_f32 v[144:145], v[40:41], v[98:99] op_sel_hi:[1,0]
	v_pk_mul_f32 v[206:207], v[84:85], v[206:207]
	v_pk_mul_f32 v[208:209], v[86:87], v[208:209]
	v_pk_mul_f32 v[142:143], v[4:5], v[142:143]
	v_pk_mul_f32 v[144:145], v[6:7], v[144:145]
	s_nop 1
	v_mov_b32_dpp v210, v206 quad_perm:[1,0,3,2] row_mask:0xf bank_mask:0xf
	v_mov_b32_dpp v211, v207 quad_perm:[1,0,3,2] row_mask:0xf bank_mask:0xf
	v_mov_b32_dpp v212, v208 quad_perm:[1,0,3,2] row_mask:0xf bank_mask:0xf
	v_mov_b32_dpp v213, v209 quad_perm:[1,0,3,2] row_mask:0xf bank_mask:0xf
	s_nop 0
	v_cndmask_b32_e64 v214, v210, v142, s[8:9]
	v_cndmask_b32_e64 v218, v142, v210, s[8:9]
	v_cndmask_b32_e64 v215, v211, v143, s[8:9]
	v_cndmask_b32_e64 v219, v143, v211, s[8:9]
	v_cndmask_b32_e64 v216, v212, v144, s[8:9]
	v_cndmask_b32_e64 v220, v144, v212, s[8:9]
	v_cndmask_b32_e64 v217, v213, v145, s[8:9]
	v_cndmask_b32_e64 v221, v145, v213, s[8:9]
	global_store_dwordx4 v[224:225], v[214:217], off offset:512
	global_store_dwordx4 v[226:227], v[218:221], off offset:512
	v_add_u32_e32 v222, 0xa0, v196
	v_ashrrev_i32_e32 v223, 31, v222
	v_lshlrev_b64 v[222:223], 13, v[222:223]
	v_lshl_add_u64 v[222:223], s[6:7], 0, v[222:223]
	v_lshl_add_u64 v[222:223], v[222:223], 0, v[194:195]
	v_lshl_add_u64 v[224:225], v[222:223], 0, v[228:229]
	v_lshl_add_u64 v[226:227], v[222:223], 0, v[230:231]
	v_pk_mul_f32 v[108:109], v[26:27], v[100:101] op_sel_hi:[1,0]
	v_pk_mul_f32 v[110:111], v[28:29], v[100:101] op_sel_hi:[1,0]
	v_pk_mul_f32 v[104:105], v[30:31], v[100:101] op_sel_hi:[1,0]
	v_pk_mul_f32 v[106:107], v[32:33], v[100:101] op_sel_hi:[1,0]
	v_pk_mul_f32 v[108:109], v[8:9], v[108:109]
	v_pk_mul_f32 v[110:111], v[10:11], v[110:111]
	v_pk_mul_f32 v[104:105], v[12:13], v[104:105]
	v_pk_mul_f32 v[106:107], v[14:15], v[106:107]
	s_nop 1
	v_mov_b32_dpp v130, v108 quad_perm:[1,0,3,2] row_mask:0xf bank_mask:0xf
	v_mov_b32_dpp v131, v109 quad_perm:[1,0,3,2] row_mask:0xf bank_mask:0xf
	v_mov_b32_dpp v132, v110 quad_perm:[1,0,3,2] row_mask:0xf bank_mask:0xf
	v_mov_b32_dpp v133, v111 quad_perm:[1,0,3,2] row_mask:0xf bank_mask:0xf
	s_nop 0
	v_cndmask_b32_e64 v134, v130, v104, s[8:9]
	v_cndmask_b32_e64 v138, v104, v130, s[8:9]
	v_cndmask_b32_e64 v135, v131, v105, s[8:9]
	v_cndmask_b32_e64 v139, v105, v131, s[8:9]
	v_cndmask_b32_e64 v136, v132, v106, s[8:9]
	v_cndmask_b32_e64 v140, v106, v132, s[8:9]
	v_cndmask_b32_e64 v137, v133, v107, s[8:9]
	v_cndmask_b32_e64 v141, v107, v133, s[8:9]
	global_store_dwordx4 v[224:225], v[134:137], off
	global_store_dwordx4 v[226:227], v[138:141], off
	v_pk_mul_f32 v[206:207], v[82:83], v[100:101] op_sel_hi:[1,0]
	v_pk_mul_f32 v[208:209], v[16:17], v[100:101] op_sel_hi:[1,0]
	v_pk_mul_f32 v[142:143], v[22:23], v[100:101] op_sel_hi:[1,0]
	v_pk_mul_f32 v[144:145], v[24:25], v[100:101] op_sel_hi:[1,0]
	v_pk_mul_f32 v[206:207], v[84:85], v[206:207]
	v_pk_mul_f32 v[208:209], v[86:87], v[208:209]
	v_pk_mul_f32 v[142:143], v[4:5], v[142:143]
	v_pk_mul_f32 v[144:145], v[6:7], v[144:145]
	s_nop 1
	v_mov_b32_dpp v210, v206 quad_perm:[1,0,3,2] row_mask:0xf bank_mask:0xf
	v_mov_b32_dpp v211, v207 quad_perm:[1,0,3,2] row_mask:0xf bank_mask:0xf
	v_mov_b32_dpp v212, v208 quad_perm:[1,0,3,2] row_mask:0xf bank_mask:0xf
	v_mov_b32_dpp v213, v209 quad_perm:[1,0,3,2] row_mask:0xf bank_mask:0xf
	s_nop 0
	v_cndmask_b32_e64 v214, v210, v142, s[8:9]
	v_cndmask_b32_e64 v218, v142, v210, s[8:9]
	v_cndmask_b32_e64 v215, v211, v143, s[8:9]
	v_cndmask_b32_e64 v219, v143, v211, s[8:9]
	v_cndmask_b32_e64 v216, v212, v144, s[8:9]
	v_cndmask_b32_e64 v220, v144, v212, s[8:9]
	v_cndmask_b32_e64 v217, v213, v145, s[8:9]
	v_cndmask_b32_e64 v221, v145, v213, s[8:9]
	global_store_dwordx4 v[224:225], v[214:217], off offset:512
	global_store_dwordx4 v[226:227], v[218:221], off offset:512
	v_add_u32_e32 v222, 0xb0, v196
	v_ashrrev_i32_e32 v223, 31, v222
	v_lshlrev_b64 v[222:223], 13, v[222:223]
	v_lshl_add_u64 v[222:223], s[6:7], 0, v[222:223]
	v_lshl_add_u64 v[222:223], v[222:223], 0, v[194:195]
	v_lshl_add_u64 v[224:225], v[222:223], 0, v[228:229]
	v_lshl_add_u64 v[226:227], v[222:223], 0, v[230:231]
	v_pk_mul_f32 v[108:109], v[74:75], v[102:103] op_sel_hi:[1,0]
	v_pk_mul_f32 v[110:111], v[18:19], v[102:103] op_sel_hi:[1,0]
	v_pk_mul_f32 v[104:105], v[78:79], v[102:103] op_sel_hi:[1,0]
	v_pk_mul_f32 v[106:107], v[20:21], v[102:103] op_sel_hi:[1,0]
	v_pk_mul_f32 v[108:109], v[8:9], v[108:109]
	v_pk_mul_f32 v[110:111], v[10:11], v[110:111]
	v_pk_mul_f32 v[104:105], v[12:13], v[104:105]
	v_pk_mul_f32 v[106:107], v[14:15], v[106:107]
	s_nop 1
	v_mov_b32_dpp v130, v108 quad_perm:[1,0,3,2] row_mask:0xf bank_mask:0xf
	v_mov_b32_dpp v131, v109 quad_perm:[1,0,3,2] row_mask:0xf bank_mask:0xf
	v_mov_b32_dpp v132, v110 quad_perm:[1,0,3,2] row_mask:0xf bank_mask:0xf
	v_mov_b32_dpp v133, v111 quad_perm:[1,0,3,2] row_mask:0xf bank_mask:0xf
	s_nop 0
	v_cndmask_b32_e64 v134, v130, v104, s[8:9]
	v_cndmask_b32_e64 v138, v104, v130, s[8:9]
	v_cndmask_b32_e64 v135, v131, v105, s[8:9]
	v_cndmask_b32_e64 v139, v105, v131, s[8:9]
	v_cndmask_b32_e64 v136, v132, v106, s[8:9]
	v_cndmask_b32_e64 v140, v106, v132, s[8:9]
	v_cndmask_b32_e64 v137, v133, v107, s[8:9]
	v_cndmask_b32_e64 v141, v107, v133, s[8:9]
	global_store_dwordx4 v[224:225], v[134:137], off
	global_store_dwordx4 v[226:227], v[138:141], off
	v_pk_mul_f32 v[206:207], v[66:67], v[102:103] op_sel_hi:[1,0]
	v_pk_mul_f32 v[208:209], v[68:69], v[102:103] op_sel_hi:[1,0]
	v_pk_mul_f32 v[142:143], v[70:71], v[102:103] op_sel_hi:[1,0]
	v_pk_mul_f32 v[144:145], v[72:73], v[102:103] op_sel_hi:[1,0]
	v_pk_mul_f32 v[206:207], v[84:85], v[206:207]
	v_pk_mul_f32 v[208:209], v[86:87], v[208:209]
	v_pk_mul_f32 v[142:143], v[4:5], v[142:143]
	v_pk_mul_f32 v[144:145], v[6:7], v[144:145]
	s_nop 1
	v_mov_b32_dpp v210, v206 quad_perm:[1,0,3,2] row_mask:0xf bank_mask:0xf
	v_mov_b32_dpp v211, v207 quad_perm:[1,0,3,2] row_mask:0xf bank_mask:0xf
	v_mov_b32_dpp v212, v208 quad_perm:[1,0,3,2] row_mask:0xf bank_mask:0xf
	v_mov_b32_dpp v213, v209 quad_perm:[1,0,3,2] row_mask:0xf bank_mask:0xf
	s_nop 0
	v_cndmask_b32_e64 v214, v210, v142, s[8:9]
	v_cndmask_b32_e64 v218, v142, v210, s[8:9]
	v_cndmask_b32_e64 v215, v211, v143, s[8:9]
	v_cndmask_b32_e64 v219, v143, v211, s[8:9]
	v_cndmask_b32_e64 v216, v212, v144, s[8:9]
	v_cndmask_b32_e64 v220, v144, v212, s[8:9]
	v_cndmask_b32_e64 v217, v213, v145, s[8:9]
	v_cndmask_b32_e64 v221, v145, v213, s[8:9]
	global_store_dwordx4 v[224:225], v[214:217], off offset:512
	global_store_dwordx4 v[226:227], v[218:221], off offset:512
